# plus: rowsum-exchange barriers wait lgkmcnt only (no vmcnt drain) in G1/G4 epilogues
# speedup vs baseline: 1.0125x; 1.0055x over previous
; #define LAS __attribute__((address_space(3)))
; #define GAS __attribute__((address_space(1)))
; DI u32x4 pack8(const f32x4 a, const f32x4 b) { return (u32x4){pk2(a.x, a.y), pk2(a.z, a.w), pk2(b.x, b.y), pk2(b.z, b.w)}; }
; DI float sq4(const f32x4 a) { return (a.x * a.x + a.y * a.y) + (a.z * a.z + a.w * a.w); }
;   DI void operator()(const acc_t& acc, const Unit& u, int, int, int, int) const {
;     ...
;       float ss[2][4];
; #pragma unroll
;       for (int ai = 0; ai < 2; ++ai)
; #pragma unroll
;         for (int m = 0; m < 4; ++m) ss[ai][m] = (sq4(acc[ai][0][m][0]) + sq4(acc[ai][0][m][1])) + (sq4(acc[ai][1][m][0]) + sq4(acc[ai][1][m][1]));
;       rowsum_xch(ss, (LAS float*)(lds + XCH_OFF), wr, wc, fr, fq);
;       GAS float* ofb = out_ + (samp ? O_CKVS : O_CKVP) + c8;
;       GAS u16* base = (GAS u16*)(ws_ + OFF_CKV) + c8;
;       f32x4 gv[2][2];
; #pragma unroll
;       for (int bj = 0; bj < 2; ++bj)
; #pragma unroll
;         for (int n = 0; n < 2; ++n) gv[bj][n] = *(const f32x4*)(p.kv_norm_g + bj * 128 + c8 + 4 * n);
; #pragma unroll
;       for (int ai = 0; ai < 2; ++ai)
; #pragma unroll
;         for (int m = 0; m < 4; ++m) {
;           const float r = rsqrtf(ss[ai][m] * (1.f / 256.f) + EPS);
;           GAS float* of = ofb + (size_t)(rl0 + ai * 128 + m * 16) * 256; GAS u16* rp = base + (size_t)(row0 + ai * 128 + m * 16) * 256;
; #pragma unroll
;           for (int bj = 0; bj < 2; ++bj) {
;             const f32x4 a = acc[ai][bj][m][0] * r * gv[bj][0], b = acc[ai][bj][m][1] * r * gv[bj][1];
;             *(GAS f32x4*)(of + bj * 128) = a; *(GAS f32x4*)(of + bj * 128 + 4) = b;
;             *(GAS u32x4*)(rp + bj * 128) = pack8(a, b);
;           }
.LBB0_205:
	s_or_b64 exec, exec, s[4:5]
	s_add_i32 s4, 16, 0x20000
	v_add3_u32 v130, s4, v167, v165
	s_waitcnt lgkmcnt(0)
	s_barrier
	ds_read_b128 v[130:133], v130
	v_lshlrev_b32_e32 v154, 2, v192
	global_load_dwordx4 v[138:141], v154, s[48:49]
	global_load_dwordx4 v[142:145], v154, s[48:49] offset:16
	v_add3_u32 v134, s85, v167, v165
	ds_read_b128 v[168:171], v134
	s_waitcnt lgkmcnt(1)
	v_mov_b32_e32 v134, v131
	v_mov_b32_e32 v135, v132
	v_mov_b32_e32 v131, v133
	v_pk_add_f32 v[176:177], v[134:135], v[130:131]
	v_add3_u32 v130, s86, v167, v165
	ds_read_b128 v[172:175], v130
	global_load_dwordx4 v[130:133], v154, s[48:49] offset:528
	global_load_dwordx4 v[134:137], v154, s[48:49] offset:512
	s_waitcnt lgkmcnt(1)
	v_mov_b32_e32 v178, v169
	v_mov_b32_e32 v179, v170
	v_mov_b32_e32 v169, v171
	v_pk_add_f32 v[198:199], v[178:179], v[168:169]
	v_add3_u32 v168, s87, v167, v165
	ds_read_b128 v[168:171], v168
	s_waitcnt lgkmcnt(1)
	v_mov_b32_e32 v178, v173
	v_mov_b32_e32 v179, v174
	v_mov_b32_e32 v173, v175
	v_pk_add_f32 v[206:207], v[178:179], v[172:173]
	s_waitcnt lgkmcnt(0)
	v_mov_b32_e32 v178, v169
	v_add3_u32 v169, s88, v167, v165
	v_mov_b32_e32 v179, v170
	ds_read_b128 v[172:175], v169
	v_mov_b32_e32 v169, v171
	v_pk_add_f32 v[208:209], v[178:179], v[168:169]
	v_add3_u32 v168, s89, v167, v165
	ds_read_b128 v[168:171], v168
	s_waitcnt lgkmcnt(1)
	v_mov_b32_e32 v178, v173
	v_mov_b32_e32 v179, v174
	v_mov_b32_e32 v173, v175
	v_pk_add_f32 v[178:179], v[178:179], v[172:173]
	s_waitcnt lgkmcnt(0)
	v_mov_b32_e32 v180, v169
	v_add3_u32 v169, s90, v167, v165
	v_mov_b32_e32 v181, v170
	ds_read_b128 v[172:175], v169
	v_mov_b32_e32 v169, v171
	v_add3_u32 v165, s91, v167, v165
	v_pk_add_f32 v[180:181], v[180:181], v[168:169]
	ds_read_b128 v[168:171], v165
	s_and_b64 s[4:5], s[6:7], exec
	s_mov_b32 s4, 0x25000000
	s_cselect_b32 s4, s4, 0x20400000
	s_add_u32 s4, s66, s4
	s_waitcnt lgkmcnt(1)
	v_mov_b32_e32 v182, v173
	v_mov_b32_e32 v183, v174
	v_mov_b32_e32 v173, v175
	s_addc_u32 s5, s67, 0
	v_pk_add_f32 v[172:173], v[182:183], v[172:173]
	s_waitcnt lgkmcnt(0)
	v_mov_b32_e32 v174, v169
	v_mov_b32_e32 v175, v170
	v_mov_b32_e32 v169, v171
	v_lshl_add_u64 v[182:183], s[4:5], 0, v[154:155]
	v_lshlrev_b32_e32 v154, 1, v192
	v_pk_add_f32 v[174:175], v[174:175], v[168:169]
	v_lshl_add_u64 v[168:169], s[64:65], 0, v[154:155]
	s_mov_b64 s[4:5], 0x203a8100
	v_lshl_add_u64 v[184:185], v[168:169], 0, s[4:5]
	v_mov_b32_e32 v170, v198
	v_mov_b32_e32 v171, v176
	v_mov_b32_e32 v176, v199
	s_mov_b32 s4, 0x358637bd
	v_pk_add_f32 v[170:171], v[170:171], v[176:177]
	v_mov_b64_e32 v[176:177], s[4:5]
	v_pk_fma_f32 v[210:211], v[170:171], s[22:23], v[176:177] op_sel_hi:[1,0,0]
	v_ashrrev_i32_e32 v165, 31, v164
	v_mul_f32_e32 v154, 0x4b800000, v211
	v_cmp_gt_f32_e32 vcc, s92, v211
	v_lshlrev_b64 v[170:171], 9, v[164:165]
	v_ashrrev_i32_e32 v167, 31, v166
	v_cndmask_b32_e32 v154, v211, v154, vcc
	v_rsq_f32_e32 v154, v154
	v_lshlrev_b64 v[168:169], 10, v[166:167]
	v_lshl_add_u64 v[168:169], v[182:183], 0, v[168:169]
	v_lshl_add_u64 v[170:171], v[184:185], 0, v[170:171]
	v_mul_f32_e32 v165, 0x45800000, v154
	v_cndmask_b32_e32 v154, v154, v165, vcc
	v_pk_mul_f32 v[198:199], v[126:127], v[154:155] op_sel_hi:[1,0]
	v_pk_mul_f32 v[200:201], v[128:129], v[154:155] op_sel_hi:[1,0]
	v_pk_mul_f32 v[202:203], v[122:123], v[154:155] op_sel_hi:[1,0]
	v_pk_mul_f32 v[204:205], v[124:125], v[154:155] op_sel_hi:[1,0]
	s_waitcnt vmcnt(3)
	v_pk_mul_f32 v[200:201], v[140:141], v[200:201]
	v_pk_mul_f32 v[198:199], v[138:139], v[198:199]
	s_waitcnt vmcnt(2)
	v_pk_mul_f32 v[204:205], v[144:145], v[204:205]
	v_pk_mul_f32 v[202:203], v[142:143], v[202:203]
	global_store_dwordx4 v[168:169], v[198:201], off
	global_store_dwordx4 v[168:169], v[202:205], off offset:16
	v_cmp_gt_f32_e32 vcc, s92, v210
	v_cvt_pk_bf16_f32 v198, v198, v199
	v_cvt_pk_bf16_f32 v199, v200, v201
	v_cvt_pk_bf16_f32 v200, v202, v203
	v_cvt_pk_bf16_f32 v201, v204, v205
	global_store_dwordx4 v[170:171], v[198:201], off
	v_pk_mul_f32 v[202:203], v[110:111], v[154:155] op_sel_hi:[1,0]
	v_pk_mul_f32 v[204:205], v[112:113], v[154:155] op_sel_hi:[1,0]
	v_pk_mul_f32 v[198:199], v[118:119], v[154:155] op_sel_hi:[1,0]
	v_pk_mul_f32 v[200:201], v[120:121], v[154:155] op_sel_hi:[1,0]
	s_waitcnt vmcnt(3)
; #define GAS __attribute__((address_space(1)))
; DI u32x4 pack8(const f32x4 a, const f32x4 b) { return (u32x4){pk2(a.x, a.y), pk2(a.z, a.w), pk2(b.x, b.y), pk2(b.z, b.w)}; }
;   DI void operator()(const acc_t& acc, const Unit& u, int, int, int, int) const {
;     ...
; #pragma unroll
;       for (int ai = 0; ai < 2; ++ai)
; #pragma unroll
;         for (int m = 0; m < 4; ++m) {
;           const float r = rsqrtf(ss[ai][m] * (1.f / 256.f) + EPS);
;           GAS float* of = ofb + (size_t)(rl0 + ai * 128 + m * 16) * 256; GAS u16* rp = base + (size_t)(row0 + ai * 128 + m * 16) * 256;
; #pragma unroll
;           for (int bj = 0; bj < 2; ++bj) {
;             const f32x4 a = acc[ai][bj][m][0] * r * gv[bj][0], b = acc[ai][bj][m][1] * r * gv[bj][1];
;             *(GAS f32x4*)(of + bj * 128) = a; *(GAS f32x4*)(of + bj * 128 + 4) = b;
;             *(GAS u32x4*)(rp + bj * 128) = pack8(a, b);
;           }
;         }
	v_pk_mul_f32 v[198:199], v[134:135], v[198:199]
	v_pk_mul_f32 v[200:201], v[136:137], v[200:201]
	v_pk_mul_f32 v[204:205], v[132:133], v[204:205]
	v_pk_mul_f32 v[202:203], v[130:131], v[202:203]
	v_mul_f32_e32 v154, 0x4b800000, v210
	global_store_dwordx4 v[168:169], v[198:201], off offset:512
	global_store_dwordx4 v[168:169], v[202:205], off offset:528
	v_cndmask_b32_e32 v154, v210, v154, vcc
	v_cvt_pk_bf16_f32 v198, v198, v199
	v_cvt_pk_bf16_f32 v199, v200, v201
	v_cvt_pk_bf16_f32 v200, v202, v203
	v_cvt_pk_bf16_f32 v201, v204, v205
	v_rsq_f32_e32 v154, v154
	global_store_dwordx4 v[170:171], v[198:201], off offset:256
	s_mov_b64 s[4:5], 0x10000
	v_mul_f32_e32 v165, 0x45800000, v154
	v_or_b32_e32 v198, 16, v166
	v_ashrrev_i32_e32 v199, 31, v198
	v_lshlrev_b64 v[198:199], 10, v[198:199]
	v_lshl_add_u64 v[210:211], v[182:183], 0, v[198:199]
	v_or_b32_e32 v198, 16, v164
	v_ashrrev_i32_e32 v199, 31, v198
	v_cndmask_b32_e32 v154, v154, v165, vcc
	v_lshlrev_b64 v[198:199], 9, v[198:199]
	v_lshl_add_u64 v[212:213], v[184:185], 0, v[198:199]
	v_pk_mul_f32 v[198:199], v[114:115], v[154:155] op_sel_hi:[1,0]
	v_pk_mul_f32 v[200:201], v[116:117], v[154:155] op_sel_hi:[1,0]
	v_pk_mul_f32 v[202:203], v[106:107], v[154:155] op_sel_hi:[1,0]
	v_pk_mul_f32 v[204:205], v[108:109], v[154:155] op_sel_hi:[1,0]
	v_pk_mul_f32 v[200:201], v[140:141], v[200:201]
	v_pk_mul_f32 v[198:199], v[138:139], v[198:199]
	v_pk_mul_f32 v[204:205], v[144:145], v[204:205]
	v_pk_mul_f32 v[202:203], v[142:143], v[202:203]
	global_store_dwordx4 v[210:211], v[198:201], off
	global_store_dwordx4 v[210:211], v[202:205], off offset:16
	s_nop 0
	v_cvt_pk_bf16_f32 v198, v198, v199
	v_cvt_pk_bf16_f32 v199, v200, v201
	v_cvt_pk_bf16_f32 v200, v202, v203
	v_cvt_pk_bf16_f32 v201, v204, v205
	global_store_dwordx4 v[212:213], v[198:201], off
	v_pk_mul_f32 v[202:203], v[94:95], v[154:155] op_sel_hi:[1,0]
	v_pk_mul_f32 v[204:205], v[96:97], v[154:155] op_sel_hi:[1,0]
	v_pk_mul_f32 v[198:199], v[102:103], v[154:155] op_sel_hi:[1,0]
	v_pk_mul_f32 v[200:201], v[104:105], v[154:155] op_sel_hi:[1,0]
	v_pk_mul_f32 v[198:199], v[134:135], v[198:199]
	v_pk_mul_f32 v[200:201], v[136:137], v[200:201]
	v_pk_mul_f32 v[204:205], v[132:133], v[204:205]
	v_pk_mul_f32 v[202:203], v[130:131], v[202:203]
	global_store_dwordx4 v[210:211], v[198:201], off offset:512
	global_store_dwordx4 v[210:211], v[202:205], off offset:528
	s_nop 0
	v_cvt_pk_bf16_f32 v198, v198, v199
	v_cvt_pk_bf16_f32 v199, v200, v201
	v_cvt_pk_bf16_f32 v200, v202, v203
	v_cvt_pk_bf16_f32 v201, v204, v205
	global_store_dwordx4 v[212:213], v[198:201], off offset:256
	s_nop 1
	v_mov_b32_e32 v200, v208
	v_mov_b32_e32 v201, v206
	v_mov_b32_e32 v206, v209
	v_pk_add_f32 v[200:201], v[200:201], v[206:207]
	v_or_b32_e32 v198, 32, v166
	v_pk_fma_f32 v[206:207], v[200:201], s[22:23], v[176:177] op_sel_hi:[1,0,0]
	v_ashrrev_i32_e32 v199, 31, v198
	v_mul_f32_e32 v154, 0x4b800000, v207
	v_cmp_gt_f32_e32 vcc, s92, v207
	v_lshlrev_b64 v[198:199], 10, v[198:199]
	v_lshl_add_u64 v[210:211], v[182:183], 0, v[198:199]
	v_cndmask_b32_e32 v154, v207, v154, vcc
	v_rsq_f32_e32 v154, v154
	v_or_b32_e32 v198, 32, v164
	v_ashrrev_i32_e32 v199, 31, v198
	v_lshlrev_b64 v[198:199], 9, v[198:199]
	v_mul_f32_e32 v165, 0x45800000, v154
	v_cndmask_b32_e32 v154, v154, v165, vcc
	v_lshl_add_u64 v[208:209], v[184:185], 0, v[198:199]
	v_pk_mul_f32 v[198:199], v[98:99], v[154:155] op_sel_hi:[1,0]
	v_pk_mul_f32 v[200:201], v[100:101], v[154:155] op_sel_hi:[1,0]
	v_pk_mul_f32 v[202:203], v[90:91], v[154:155] op_sel_hi:[1,0]
	v_pk_mul_f32 v[204:205], v[92:93], v[154:155] op_sel_hi:[1,0]
	v_pk_mul_f32 v[200:201], v[140:141], v[200:201]
	v_pk_mul_f32 v[198:199], v[138:139], v[198:199]
	v_pk_mul_f32 v[204:205], v[144:145], v[204:205]
	v_pk_mul_f32 v[202:203], v[142:143], v[202:203]
	global_store_dwordx4 v[210:211], v[198:201], off
	global_store_dwordx4 v[210:211], v[202:205], off offset:16
	v_cmp_gt_f32_e32 vcc, s92, v206
	v_cvt_pk_bf16_f32 v198, v198, v199
	v_cvt_pk_bf16_f32 v199, v200, v201
	v_cvt_pk_bf16_f32 v200, v202, v203
	v_cvt_pk_bf16_f32 v201, v204, v205
	global_store_dwordx4 v[208:209], v[198:201], off
	v_pk_mul_f32 v[202:203], v[78:79], v[154:155] op_sel_hi:[1,0]
	v_pk_mul_f32 v[204:205], v[80:81], v[154:155] op_sel_hi:[1,0]
	v_pk_mul_f32 v[198:199], v[86:87], v[154:155] op_sel_hi:[1,0]
	v_pk_mul_f32 v[200:201], v[88:89], v[154:155] op_sel_hi:[1,0]
	v_pk_mul_f32 v[198:199], v[134:135], v[198:199]
	v_pk_mul_f32 v[200:201], v[136:137], v[200:201]
	v_pk_mul_f32 v[204:205], v[132:133], v[204:205]
	v_pk_mul_f32 v[202:203], v[130:131], v[202:203]
	v_mul_f32_e32 v154, 0x4b800000, v206
	global_store_dwordx4 v[210:211], v[198:201], off offset:512
	global_store_dwordx4 v[210:211], v[202:205], off offset:528
	v_cndmask_b32_e32 v154, v206, v154, vcc
	v_cvt_pk_bf16_f32 v198, v198, v199
	v_cvt_pk_bf16_f32 v199, v200, v201
	v_cvt_pk_bf16_f32 v200, v202, v203
	v_cvt_pk_bf16_f32 v201, v204, v205
	v_rsq_f32_e32 v154, v154
	global_store_dwordx4 v[208:209], v[198:201], off offset:256
	v_mul_f32_e32 v165, 0x45800000, v154
	s_nop 0
	v_or_b32_e32 v198, 48, v166
	v_ashrrev_i32_e32 v199, 31, v198
	v_lshlrev_b64 v[198:199], 10, v[198:199]
	v_lshl_add_u64 v[202:203], v[182:183], 0, v[198:199]
	v_or_b32_e32 v182, 48, v164
	v_ashrrev_i32_e32 v183, 31, v182
	v_cndmask_b32_e32 v154, v154, v165, vcc
	v_lshlrev_b64 v[182:183], 9, v[182:183]
	v_lshl_add_u64 v[204:205], v[184:185], 0, v[182:183]
	v_pk_mul_f32 v[182:183], v[82:83], v[154:155] op_sel_hi:[1,0]
	v_pk_mul_f32 v[184:185], v[84:85], v[154:155] op_sel_hi:[1,0]
	v_pk_mul_f32 v[198:199], v[74:75], v[154:155] op_sel_hi:[1,0]
; #define GAS __attribute__((address_space(1)))
; DI u32x4 pack8(const f32x4 a, const f32x4 b) { return (u32x4){pk2(a.x, a.y), pk2(a.z, a.w), pk2(b.x, b.y), pk2(b.z, b.w)}; }
;   DI void operator()(const acc_t& acc, const Unit& u, int, int, int, int) const {
;     ...
; #pragma unroll
;       for (int ai = 0; ai < 2; ++ai)
; #pragma unroll
;         for (int m = 0; m < 4; ++m) {
;           const float r = rsqrtf(ss[ai][m] * (1.f / 256.f) + EPS);
;           GAS float* of = ofb + (size_t)(rl0 + ai * 128 + m * 16) * 256; GAS u16* rp = base + (size_t)(row0 + ai * 128 + m * 16) * 256;
; #pragma unroll
;           for (int bj = 0; bj < 2; ++bj) {
;             const f32x4 a = acc[ai][bj][m][0] * r * gv[bj][0], b = acc[ai][bj][m][1] * r * gv[bj][1];
;             *(GAS f32x4*)(of + bj * 128) = a; *(GAS f32x4*)(of + bj * 128 + 4) = b;
;             *(GAS u32x4*)(rp + bj * 128) = pack8(a, b);
;           }
;         }
	v_pk_mul_f32 v[200:201], v[76:77], v[154:155] op_sel_hi:[1,0]
	v_pk_mul_f32 v[184:185], v[140:141], v[184:185]
	v_pk_mul_f32 v[182:183], v[138:139], v[182:183]
	v_pk_mul_f32 v[200:201], v[144:145], v[200:201]
	v_pk_mul_f32 v[198:199], v[142:143], v[198:199]
	global_store_dwordx4 v[202:203], v[182:185], off
	global_store_dwordx4 v[202:203], v[198:201], off offset:16
	s_nop 0
	v_cvt_pk_bf16_f32 v182, v182, v183
	v_cvt_pk_bf16_f32 v183, v184, v185
	v_cvt_pk_bf16_f32 v184, v198, v199
	v_cvt_pk_bf16_f32 v185, v200, v201
	global_store_dwordx4 v[204:205], v[182:185], off
	v_pk_mul_f32 v[198:199], v[66:67], v[154:155] op_sel_hi:[1,0]
	v_pk_mul_f32 v[200:201], v[68:69], v[154:155] op_sel_hi:[1,0]
	v_pk_mul_f32 v[182:183], v[70:71], v[154:155] op_sel_hi:[1,0]
	v_pk_mul_f32 v[184:185], v[72:73], v[154:155] op_sel_hi:[1,0]
	v_pk_mul_f32 v[182:183], v[134:135], v[182:183]
	v_pk_mul_f32 v[184:185], v[136:137], v[184:185]
	v_pk_mul_f32 v[198:199], v[130:131], v[198:199]
	v_pk_mul_f32 v[200:201], v[132:133], v[200:201]
	global_store_dwordx4 v[202:203], v[182:185], off offset:512
	global_store_dwordx4 v[202:203], v[198:201], off offset:528
	v_lshl_add_u64 v[202:203], v[170:171], 0, s[4:5]
	v_cvt_pk_bf16_f32 v182, v182, v183
	v_cvt_pk_bf16_f32 v183, v184, v185
	v_cvt_pk_bf16_f32 v184, v198, v199
	v_mov_b32_e32 v198, v180
	v_mov_b32_e32 v199, v178
	v_mov_b32_e32 v178, v181
	v_pk_add_f32 v[178:179], v[198:199], v[178:179]
	v_cvt_pk_bf16_f32 v185, v200, v201
	v_pk_fma_f32 v[198:199], v[178:179], s[22:23], v[176:177] op_sel_hi:[1,0,0]
	global_store_dwordx4 v[204:205], v[182:185], off offset:256
	v_mul_f32_e32 v154, 0x4b800000, v199
	v_cmp_gt_f32_e32 vcc, s92, v199
	s_mov_b32 s4, 0x10000
	v_lshl_add_u64 v[200:201], v[168:169], 0, s[24:25]
	v_cndmask_b32_e32 v154, v199, v154, vcc
	v_rsq_f32_e32 v154, v154
	s_nop 0
	v_mul_f32_e32 v165, 0x45800000, v154
	v_cndmask_b32_e32 v154, v154, v165, vcc
	v_pk_mul_f32 v[178:179], v[62:63], v[154:155] op_sel_hi:[1,0]
	v_pk_mul_f32 v[180:181], v[64:65], v[154:155] op_sel_hi:[1,0]
	v_pk_mul_f32 v[182:183], v[58:59], v[154:155] op_sel_hi:[1,0]
	v_add_co_u32_e32 v204, vcc, s84, v168
	v_pk_mul_f32 v[180:181], v[140:141], v[180:181]
	v_pk_mul_f32 v[178:179], v[138:139], v[178:179]
	v_pk_mul_f32 v[184:185], v[60:61], v[154:155] op_sel_hi:[1,0]
	v_pk_mul_f32 v[182:183], v[142:143], v[182:183]
	v_addc_co_u32_e32 v205, vcc, 0, v169, vcc
	v_pk_mul_f32 v[184:185], v[144:145], v[184:185]
	global_store_dwordx4 v[204:205], v[178:181], off
	global_store_dwordx4 v[200:201], v[182:185], off offset:16
	s_nop 0
	v_cvt_pk_bf16_f32 v178, v178, v179
	v_cvt_pk_bf16_f32 v179, v180, v181
	v_cvt_pk_bf16_f32 v180, v182, v183
	v_add_co_u32_e32 v182, vcc, s4, v170
	v_cvt_pk_bf16_f32 v181, v184, v185
	s_nop 0
	v_addc_co_u32_e32 v183, vcc, 0, v171, vcc
	global_store_dwordx4 v[182:183], v[178:181], off
	v_pk_mul_f32 v[182:183], v[42:43], v[154:155] op_sel_hi:[1,0]
	v_pk_mul_f32 v[184:185], v[44:45], v[154:155] op_sel_hi:[1,0]
	v_pk_mul_f32 v[178:179], v[50:51], v[154:155] op_sel_hi:[1,0]
	v_pk_mul_f32 v[180:181], v[52:53], v[154:155] op_sel_hi:[1,0]
	v_mul_f32_e32 v154, 0x4b800000, v198
	v_cmp_gt_f32_e32 vcc, s92, v198
	v_pk_mul_f32 v[180:181], v[136:137], v[180:181]
	v_pk_mul_f32 v[178:179], v[134:135], v[178:179]
	v_cndmask_b32_e32 v154, v198, v154, vcc
	v_rsq_f32_e32 v154, v154
	v_pk_mul_f32 v[184:185], v[132:133], v[184:185]
	v_pk_mul_f32 v[182:183], v[130:131], v[182:183]
	global_store_dwordx4 v[200:201], v[178:181], off offset:512
	global_store_dwordx4 v[200:201], v[182:185], off offset:528
	v_mul_f32_e32 v165, 0x45800000, v154
	v_cvt_pk_bf16_f32 v178, v178, v179
	v_cvt_pk_bf16_f32 v179, v180, v181
	v_cvt_pk_bf16_f32 v180, v182, v183
	v_cvt_pk_bf16_f32 v181, v184, v185
	v_cndmask_b32_e32 v154, v154, v165, vcc
	global_store_dwordx4 v[202:203], v[178:181], off offset:256
	s_mov_b64 s[4:5], 0x12000
	v_pk_mul_f32 v[182:183], v[46:47], v[154:155] op_sel_hi:[1,0]
	v_pk_mul_f32 v[178:179], v[54:55], v[154:155] op_sel_hi:[1,0]
	v_pk_mul_f32 v[180:181], v[56:57], v[154:155] op_sel_hi:[1,0]
	v_add_co_u32_e32 v202, vcc, s93, v168
	v_lshl_add_u64 v[200:201], v[170:171], 0, s[4:5]
	v_pk_mul_f32 v[180:181], v[140:141], v[180:181]
	v_pk_mul_f32 v[178:179], v[138:139], v[178:179]
	v_pk_mul_f32 v[184:185], v[48:49], v[154:155] op_sel_hi:[1,0]
	v_pk_mul_f32 v[182:183], v[142:143], v[182:183]
	v_addc_co_u32_e32 v203, vcc, 0, v169, vcc
	s_mov_b32 s4, 0x12000
	v_lshl_add_u64 v[198:199], v[168:169], 0, s[26:27]
	v_pk_mul_f32 v[184:185], v[144:145], v[184:185]
	global_store_dwordx4 v[202:203], v[178:181], off
	global_store_dwordx4 v[198:199], v[182:185], off offset:16
	s_nop 0
	v_cvt_pk_bf16_f32 v178, v178, v179
	v_cvt_pk_bf16_f32 v179, v180, v181
	v_cvt_pk_bf16_f32 v180, v182, v183
	v_add_co_u32_e32 v182, vcc, s4, v170
	v_cvt_pk_bf16_f32 v181, v184, v185
	s_nop 0
	v_addc_co_u32_e32 v183, vcc, 0, v171, vcc
	global_store_dwordx4 v[182:183], v[178:181], off
	v_pk_mul_f32 v[182:183], v[26:27], v[154:155] op_sel_hi:[1,0]
	v_pk_mul_f32 v[184:185], v[28:29], v[154:155] op_sel_hi:[1,0]
; #define GAS __attribute__((address_space(1)))
; DI u32x4 pack8(const f32x4 a, const f32x4 b) { return (u32x4){pk2(a.x, a.y), pk2(a.z, a.w), pk2(b.x, b.y), pk2(b.z, b.w)}; }
;   DI void operator()(const acc_t& acc, const Unit& u, int, int, int, int) const {
;     ...
; #pragma unroll
;       for (int ai = 0; ai < 2; ++ai)
; #pragma unroll
;         for (int m = 0; m < 4; ++m) {
;           const float r = rsqrtf(ss[ai][m] * (1.f / 256.f) + EPS);
;           GAS float* of = ofb + (size_t)(rl0 + ai * 128 + m * 16) * 256; GAS u16* rp = base + (size_t)(row0 + ai * 128 + m * 16) * 256;
; #pragma unroll
;           for (int bj = 0; bj < 2; ++bj) {
;             const f32x4 a = acc[ai][bj][m][0] * r * gv[bj][0], b = acc[ai][bj][m][1] * r * gv[bj][1];
;             *(GAS f32x4*)(of + bj * 128) = a; *(GAS f32x4*)(of + bj * 128 + 4) = b;
;             *(GAS u32x4*)(rp + bj * 128) = pack8(a, b);
;           }
;         }
	v_pk_mul_f32 v[178:179], v[34:35], v[154:155] op_sel_hi:[1,0]
	v_pk_mul_f32 v[180:181], v[36:37], v[154:155] op_sel_hi:[1,0]
	v_pk_mul_f32 v[178:179], v[134:135], v[178:179]
	v_pk_mul_f32 v[180:181], v[136:137], v[180:181]
	v_pk_mul_f32 v[182:183], v[130:131], v[182:183]
	v_pk_mul_f32 v[184:185], v[132:133], v[184:185]
	global_store_dwordx4 v[198:199], v[178:181], off offset:512
	global_store_dwordx4 v[198:199], v[182:185], off offset:528
	s_mov_b64 s[4:5], 0x14000
	v_cvt_pk_bf16_f32 v178, v178, v179
	v_cvt_pk_bf16_f32 v179, v180, v181
	v_cvt_pk_bf16_f32 v180, v182, v183
	v_mov_b32_e32 v182, v174
	v_mov_b32_e32 v183, v172
	v_mov_b32_e32 v172, v175
	v_pk_add_f32 v[172:173], v[182:183], v[172:173]
	v_cvt_pk_bf16_f32 v181, v184, v185
	v_pk_fma_f32 v[182:183], v[172:173], s[22:23], v[176:177] op_sel_hi:[1,0,0]
	global_store_dwordx4 v[200:201], v[178:181], off offset:256
	v_mul_f32_e32 v154, 0x4b800000, v183
	v_cmp_gt_f32_e32 vcc, s92, v183
	v_lshl_add_u64 v[184:185], v[170:171], 0, s[4:5]
	s_mov_b32 s4, 0x14000
	v_cndmask_b32_e32 v154, v183, v154, vcc
	v_rsq_f32_e32 v154, v154
	v_lshl_add_u64 v[180:181], v[168:169], 0, s[34:35]
	v_mul_f32_e32 v165, 0x45800000, v154
	v_cndmask_b32_e32 v154, v154, v165, vcc
	v_pk_mul_f32 v[172:173], v[38:39], v[154:155] op_sel_hi:[1,0]
	v_pk_mul_f32 v[174:175], v[40:41], v[154:155] op_sel_hi:[1,0]
	v_pk_mul_f32 v[176:177], v[30:31], v[154:155] op_sel_hi:[1,0]
	v_add_co_u32_e32 v198, vcc, s94, v168
	v_pk_mul_f32 v[174:175], v[140:141], v[174:175]
	v_pk_mul_f32 v[172:173], v[138:139], v[172:173]
	v_pk_mul_f32 v[178:179], v[32:33], v[154:155] op_sel_hi:[1,0]
	v_pk_mul_f32 v[176:177], v[142:143], v[176:177]
	v_addc_co_u32_e32 v199, vcc, 0, v169, vcc
	v_pk_mul_f32 v[178:179], v[144:145], v[178:179]
	global_store_dwordx4 v[198:199], v[172:175], off
	global_store_dwordx4 v[180:181], v[176:179], off offset:16
	s_nop 0
	v_cvt_pk_bf16_f32 v172, v172, v173
	v_cvt_pk_bf16_f32 v173, v174, v175
	v_cvt_pk_bf16_f32 v174, v176, v177
	v_add_co_u32_e32 v176, vcc, s4, v170
	v_cvt_pk_bf16_f32 v175, v178, v179
	s_nop 0
	v_addc_co_u32_e32 v177, vcc, 0, v171, vcc
	global_store_dwordx4 v[176:177], v[172:175], off
	v_pk_mul_f32 v[176:177], v[10:11], v[154:155] op_sel_hi:[1,0]
	v_pk_mul_f32 v[178:179], v[12:13], v[154:155] op_sel_hi:[1,0]
	v_pk_mul_f32 v[172:173], v[18:19], v[154:155] op_sel_hi:[1,0]
	v_pk_mul_f32 v[174:175], v[20:21], v[154:155] op_sel_hi:[1,0]
	v_mul_f32_e32 v154, 0x4b800000, v182
	v_cmp_gt_f32_e32 vcc, s92, v182
	v_pk_mul_f32 v[174:175], v[136:137], v[174:175]
	v_pk_mul_f32 v[172:173], v[134:135], v[172:173]
	v_cndmask_b32_e32 v154, v182, v154, vcc
	v_rsq_f32_e32 v154, v154
	v_pk_mul_f32 v[178:179], v[132:133], v[178:179]
	v_pk_mul_f32 v[176:177], v[130:131], v[176:177]
	global_store_dwordx4 v[180:181], v[172:175], off offset:512
	global_store_dwordx4 v[180:181], v[176:179], off offset:528
	v_mul_f32_e32 v165, 0x45800000, v154
	v_cndmask_b32_e32 v154, v154, v165, vcc
	v_cvt_pk_bf16_f32 v172, v172, v173
	v_cvt_pk_bf16_f32 v173, v174, v175
	v_cvt_pk_bf16_f32 v174, v176, v177
	v_cvt_pk_bf16_f32 v175, v178, v179
	v_pk_mul_f32 v[176:177], v[22:23], v[154:155] op_sel_hi:[1,0]
	global_store_dwordx4 v[184:185], v[172:175], off offset:256
	s_mov_b64 s[4:5], 0x16000
	v_pk_mul_f32 v[178:179], v[24:25], v[154:155] op_sel_hi:[1,0]
	v_lshl_add_u64 v[172:173], v[168:169], 0, s[36:37]
	v_pk_mul_f32 v[138:139], v[138:139], v[176:177]
	v_pk_mul_f32 v[176:177], v[14:15], v[154:155] op_sel_hi:[1,0]
	v_add_co_u32_e32 v168, vcc, s95, v168
	v_lshl_add_u64 v[174:175], v[170:171], 0, s[4:5]
	v_pk_mul_f32 v[140:141], v[140:141], v[178:179]
	v_pk_mul_f32 v[178:179], v[16:17], v[154:155] op_sel_hi:[1,0]
	v_pk_mul_f32 v[142:143], v[142:143], v[176:177]
	v_addc_co_u32_e32 v169, vcc, 0, v169, vcc
	s_mov_b32 s4, 0x16000
	v_pk_mul_f32 v[144:145], v[144:145], v[178:179]
	global_store_dwordx4 v[168:169], v[138:141], off
	global_store_dwordx4 v[172:173], v[142:145], off offset:16
	s_nop 0
	v_cvt_pk_bf16_f32 v138, v138, v139
	v_cvt_pk_bf16_f32 v139, v140, v141
	v_cvt_pk_bf16_f32 v140, v142, v143
	v_add_co_u32_e32 v142, vcc, s4, v170
	v_cvt_pk_bf16_f32 v141, v144, v145
	s_nop 0
	v_addc_co_u32_e32 v143, vcc, 0, v171, vcc
	global_store_dwordx4 v[142:143], v[138:141], off
	s_mov_b64 s[4:5], 0
	s_nop 0
	v_pk_mul_f32 v[138:139], v[6:7], v[154:155] op_sel_hi:[1,0]
	v_pk_mul_f32 v[140:141], v[8:9], v[154:155] op_sel_hi:[1,0]
	v_pk_mul_f32 v[134:135], v[134:135], v[138:139]
	v_pk_mul_f32 v[136:137], v[136:137], v[140:141]
	v_pk_mul_f32 v[138:139], v[2:3], v[154:155] op_sel_hi:[1,0]
	v_pk_mul_f32 v[140:141], v[4:5], v[154:155] op_sel_hi:[1,0]
	v_pk_mul_f32 v[130:131], v[130:131], v[138:139]
	v_pk_mul_f32 v[132:133], v[132:133], v[140:141]
	global_store_dwordx4 v[172:173], v[134:137], off offset:512
	global_store_dwordx4 v[172:173], v[130:133], off offset:528
	s_nop 0
	v_cvt_pk_bf16_f32 v134, v134, v135
	v_cvt_pk_bf16_f32 v135, v136, v137
	v_cvt_pk_bf16_f32 v136, v130, v131
	v_cvt_pk_bf16_f32 v137, v132, v133
	global_store_dwordx4 v[174:175], v[134:137], off offset:256

; #define LAS __attribute__((address_space(3)))
; #define GAS __attribute__((address_space(1)))
;   DI void operator()(const acc_t& acc, const Unit& u, int, int, int, int) const {
;     ...
;       rowsum_xch(ss, (LAS float*)(lds + XCH_OFF), wr, wc, fr, fq);
;       GAS float* cqss = (GAS float*)(ws_ + OFF_CQSS) + (size_t)part * NTOK;
;       if (wc == 0 && fq == 0) {
; #pragma unroll
;         for (int ai = 0; ai < 2; ++ai)
; #pragma unroll
;           for (int m = 0; m < 4; ++m) cqss[row0 + ai * 128 + m * 16] = ss[ai][m];
;       }
.LBB0_227:
	s_or_b64 exec, exec, s[68:69]
	s_lshr_b32 s20, s20, 6
	v_lshrrev_b32_e32 v132, 4, v195
	v_bitop3_b32 v132, s20, 3, v132 bitop3:0xc8
	v_cmp_ne_u32_e32 vcc, 0, v132
	s_waitcnt lgkmcnt(0)
	s_barrier
	s_and_saveexec_b64 s[68:69], vcc
	s_xor_b64 s[68:69], exec, s[68:69]
	v_ashrrev_i32_e32 v165, 31, v164
	s_andn2_saveexec_b64 s[68:69], s[68:69]
	s_cbranch_execz .LBB0_231
	v_add3_u32 v132, s91, v131, v130
	ds_read_b128 v[132:135], v132
	v_readlane_b32 s70, v228, 0
	v_readlane_b32 s71, v228, 1
	s_mul_i32 s70, s21, 0x10400
	s_mov_b32 s53, s71
	s_waitcnt lgkmcnt(0)
	v_add_f32_e32 v132, v132, v133
	v_add_f32_e32 v133, v134, v135
	v_add_f32_e32 v136, v132, v133
	v_add3_u32 v132, s90, v131, v130
	ds_read_b128 v[132:135], v132
	s_lshl_b64 s[70:71], s[70:71], 2
	s_add_u32 s70, s64, s70
	s_addc_u32 s71, s65, s71
	s_add_i32 s20, 16, 0x20000
	s_waitcnt lgkmcnt(0)
	v_add_f32_e32 v132, v132, v133
	v_add_f32_e32 v133, v134, v135
	v_add_f32_e32 v137, v132, v133
	v_add3_u32 v132, s89, v131, v130
	ds_read_b128 v[132:135], v132
	v_ashrrev_i32_e32 v165, 31, v164
	v_writelane_b32 v228, s52, 0
	s_waitcnt lgkmcnt(0)
	v_add_f32_e32 v132, v132, v133
	v_add_f32_e32 v133, v134, v135
	v_add_f32_e32 v138, v132, v133
	v_add3_u32 v132, s88, v131, v130
	ds_read_b128 v[132:135], v132
	v_writelane_b32 v228, s53, 1
	s_waitcnt lgkmcnt(0)
	v_add_f32_e32 v132, v132, v133
	v_add_f32_e32 v133, v134, v135
	v_add_f32_e32 v139, v132, v133
	v_add3_u32 v132, s87, v131, v130
	ds_read_b128 v[132:135], v132
	s_waitcnt lgkmcnt(0)
	v_add_f32_e32 v132, v132, v133
	v_add_f32_e32 v133, v134, v135
	v_add_f32_e32 v140, v132, v133
	v_add3_u32 v132, s86, v131, v130
	ds_read_b128 v[132:135], v132
	s_waitcnt lgkmcnt(0)
	v_add_f32_e32 v132, v132, v133
	v_add_f32_e32 v133, v134, v135
	v_add_f32_e32 v141, v132, v133
	v_add3_u32 v132, s85, v131, v130
	ds_read_b128 v[132:135], v132
	v_add3_u32 v130, s20, v131, v130
	s_waitcnt lgkmcnt(0)
	v_add_f32_e32 v132, v132, v133
	v_add_f32_e32 v133, v134, v135
	v_add_f32_e32 v134, v132, v133
	ds_read_b128 v[130:133], v130
	s_waitcnt lgkmcnt(0)
	v_add_f32_e32 v130, v130, v131
	v_add_f32_e32 v131, v132, v133
	v_add_f32_e32 v135, v130, v131
	v_lshl_add_u64 v[130:131], v[164:165], 2, s[70:71]
	s_mov_b64 s[70:71], 0xa62100
	v_lshl_add_u64 v[132:133], v[130:131], 0, s[70:71]
	v_add_co_u32_e32 v130, vcc, 0xa62000, v130
	s_nop 1
	v_addc_co_u32_e32 v131, vcc, 0, v131, vcc
	global_store_dword v[130:131], v135, off offset:256
	global_store_dword v[132:133], v134, off offset:64
	global_store_dword v[132:133], v141, off offset:128
	global_store_dword v[132:133], v140, off offset:192
	global_store_dword v[132:133], v139, off offset:512
	global_store_dword v[132:133], v138, off offset:576
	global_store_dword v[132:133], v137, off offset:640
	global_store_dword v[132:133], v136, off offset:704

; #define LAS __attribute__((address_space(3)))
; #define GAS __attribute__((address_space(1)))
; DI float sq4(const f32x4 a) { return (a.x * a.x + a.y * a.y) + (a.z * a.z + a.w * a.w); }
;   DI void operator()(const acc_t& acc, const Unit& u, int, int, int, int) const {
;     ...
;     float ss[2][4];
; #pragma unroll
;     for (int ai = 0; ai < 2; ++ai)
; #pragma unroll
;       for (int m = 0; m < 4; ++m) ss[ai][m] = (sq4(acc[ai][0][m][0]) + sq4(acc[ai][0][m][1])) + (sq4(acc[ai][1][m][0]) + sq4(acc[ai][1][m][1]));
;     rowsum_xch(ss, (LAS float*)(lds + XCH_OFF), wr, wc, fr, fq);
;     GAS float* rss = (GAS float*)(ws_ + OFF_ROWSS) + (size_t)u.pn * NTOK;
;     if (wc == 0 && fq == 0) {
; #pragma unroll
;       for (int ai = 0; ai < 2; ++ai)
; #pragma unroll
;         for (int m = 0; m < 4; ++m) rss[row0 + ai * 128 + m * 16] = ss[ai][m];
;     }
.LBB0_503:
	s_or_b64 exec, exec, s[26:27]
	s_lshl_b32 s22, s22, 8
	s_lshl_b32 s11, s11, 6
	s_add_i32 s11, s11, s22
	s_lshr_b32 s17, s17, 6
	v_lshrrev_b32_e32 v138, 4, v138
	s_waitcnt lgkmcnt(0)
	v_or_b32_e32 v162, s11, v150
	v_bitop3_b32 v138, s17, 3, v138 bitop3:0xc8
	v_or_b32_e32 v160, 16, v162
	v_or_b32_e32 v158, 32, v162
	v_or_b32_e32 v156, 48, v162
	v_add_u32_e32 v154, 0x80, v162
	v_add_u32_e32 v152, 0x90, v162
	v_add_u32_e32 v150, 0xa0, v162
	v_add_u32_e32 v148, 0xb0, v162
	v_cmp_ne_u32_e32 vcc, 0, v138
	v_ashrrev_i32_e32 v163, 31, v162
	v_ashrrev_i32_e32 v161, 31, v160
	v_ashrrev_i32_e32 v159, 31, v158
	v_ashrrev_i32_e32 v157, 31, v156
	v_ashrrev_i32_e32 v155, 31, v154
	v_ashrrev_i32_e32 v153, 31, v152
	v_ashrrev_i32_e32 v151, 31, v150
	v_ashrrev_i32_e32 v149, 31, v148
	s_waitcnt lgkmcnt(0)
	s_barrier
	s_and_saveexec_b64 s[22:23], vcc
	s_xor_b64 s[22:23], exec, s[22:23]
	s_andn2_saveexec_b64 s[22:23], s[22:23]
	s_cbranch_execz .LBB0_494
	v_add3_u32 v138, s53, v171, v170
	ds_read_b128 v[172:175], v138
	v_add3_u32 v138, s60, v171, v170
	ds_read_b128 v[176:179], v138
	s_mul_i32 s17, s67, 0x41000
	s_mul_hi_i32 s11, s67, 0x41000
	s_waitcnt lgkmcnt(1)
	v_add_f32_e32 v138, v172, v173
	v_add_f32_e32 v172, v174, v175
	v_add_f32_e32 v138, v138, v172
	v_add3_u32 v172, s61, v171, v170
	ds_read_b128 v[172:175], v172
	s_waitcnt lgkmcnt(1)
	v_add_f32_e32 v180, v176, v177
	v_add3_u32 v176, s62, v171, v170
	v_add_f32_e32 v181, v178, v179
	ds_read_b128 v[176:179], v176
	s_waitcnt lgkmcnt(1)
	v_add_f32_e32 v172, v172, v173
	v_add_f32_e32 v173, v174, v175
	v_add_f32_e32 v180, v180, v181
	v_add_f32_e32 v181, v172, v173
	v_add3_u32 v172, s63, v171, v170
	ds_read_b128 v[172:175], v172
	s_waitcnt lgkmcnt(1)
	v_add_f32_e32 v182, v176, v177
	v_add3_u32 v176, s64, v171, v170
	v_add_f32_e32 v183, v178, v179
	ds_read_b128 v[176:179], v176
	s_add_u32 s26, s24, s17
	s_waitcnt lgkmcnt(1)
	v_add_f32_e32 v172, v172, v173
	v_add_f32_e32 v173, v174, v175
	s_addc_u32 s27, s25, s11
	v_add_f32_e32 v182, v182, v183
	v_add_f32_e32 v183, v172, v173
	v_add3_u32 v172, s65, v171, v170
	s_add_i32 s11, 16, 0x20000
	ds_read_b128 v[172:175], v172
	v_add3_u32 v170, s11, v171, v170
	s_waitcnt lgkmcnt(1)
	v_add_f32_e32 v184, v176, v177
	v_add_f32_e32 v185, v178, v179
	ds_read_b128 v[176:179], v170
	s_waitcnt lgkmcnt(1)
	v_add_f32_e32 v170, v172, v173
	v_add_f32_e32 v171, v174, v175
	v_add_f32_e32 v174, v170, v171
	v_add_f32_e32 v184, v184, v185
	s_waitcnt lgkmcnt(0)
	v_add_f32_e32 v170, v176, v177
	v_add_f32_e32 v171, v178, v179
	v_add_f32_e32 v175, v170, v171
	v_lshl_add_u64 v[170:171], v[162:163], 2, s[26:27]
	v_lshl_add_u64 v[172:173], v[170:171], 0, s[6:7]
	v_add_co_u32_e32 v170, vcc, s66, v170
	s_nop 1
	v_addc_co_u32_e32 v171, vcc, 0, v171, vcc
	global_store_dword v[170:171], v175, off offset:256
	global_store_dword v[172:173], v174, off offset:64
	global_store_dword v[172:173], v184, off offset:128
	global_store_dword v[172:173], v183, off offset:192
	global_store_dword v[172:173], v182, off offset:512
	global_store_dword v[172:173], v181, off offset:576
	global_store_dword v[172:173], v180, off offset:640
	global_store_dword v[172:173], v138, off offset:704
	s_branch .LBB0_494
